# stand-alone RMSNorm loop: last four xor-shuffle steps of the wave reduction done with DPP moves instead of ds_bpermute (same as the phase-0 loop)
# baseline (speedup 1.0000x reference)
; __device__ __forceinline__ float shx(float v, int mask, int lane) { return __int_as_float(__builtin_amdgcn_ds_bpermute((lane ^ mask) << 2, __float_as_int(v))); }
; __device__ __forceinline__ void norm_phase(const float* __restrict__ xin, const float* __restrict__ gain, const float* __restrict__ shift, const float* __restrict__ scale, bf16_t* __restrict__ H) {
;     ...
;     for (int row = gw; row < T; row += nw) {
;         const float* xr = xin + (size_t)row * D;
;         f32x4 v[8]; float ss = 0.f;
; #pragma unroll
;         for (int i = 0; i < 8; ++i) { v[i] = *(const f32x4*)(xr + i * 256 + lane * 4); ss += v[i][0] * v[i][0] + v[i][1] * v[i][1] + v[i][2] * v[i][2] + v[i][3] * v[i][3]; }
; #pragma unroll
;         for (int o = 32; o > 0; o >>= 1) ss += shx(ss, o, lane);
.LBB0_172:
	flat_load_dwordx4 v[102:105], v[68:69]
	flat_load_dwordx4 v[106:109], v[68:69] offset:1024
	v_add_u32_e32 v116, s88, v116
	s_waitcnt vmcnt(0) lgkmcnt(0)
	v_mov_b32_e32 v112, v103
	v_mov_b32_e32 v113, v107
	v_mov_b32_e32 v110, v102
	v_mov_b32_e32 v111, v106
	v_pk_mul_f32 v[112:113], v[112:113], v[112:113]
	s_nop 0
	v_pk_fma_f32 v[114:115], v[110:111], v[110:111], v[112:113]
	flat_load_dwordx4 v[110:113], v[68:69] offset:2048
	flat_load_dwordx4 v[122:125], v[68:69] offset:3072
	s_waitcnt vmcnt(0) lgkmcnt(0)
	v_mov_b32_e32 v128, v111
	v_mov_b32_e32 v129, v123
	v_mov_b32_e32 v126, v110
	v_mov_b32_e32 v127, v122
	v_pk_mul_f32 v[128:129], v[128:129], v[128:129]
	s_nop 0
	v_pk_fma_f32 v[126:127], v[126:127], v[126:127], v[128:129]
	v_mov_b32_e32 v128, v104
	v_mov_b32_e32 v129, v108
	v_pk_fma_f32 v[114:115], v[128:129], v[128:129], v[114:115]
	v_mov_b32_e32 v128, v112
	v_mov_b32_e32 v129, v124
	v_pk_fma_f32 v[126:127], v[128:129], v[128:129], v[126:127]
	v_mov_b32_e32 v128, v105
	v_mov_b32_e32 v129, v109
	v_pk_fma_f32 v[114:115], v[128:129], v[128:129], v[114:115]
	v_mov_b32_e32 v128, v113
	v_mov_b32_e32 v129, v125
	v_pk_fma_f32 v[142:143], v[128:129], v[128:129], v[126:127]
	v_add_co_u32_e32 v126, vcc, 0xfffff000, v68
	s_nop 1
	v_addc_co_u32_e32 v127, vcc, -1, v69, vcc
	v_add_co_u32_e32 v130, vcc, 0xfffff400, v68
	s_nop 1
	v_addc_co_u32_e32 v131, vcc, -1, v69, vcc
	flat_load_dwordx4 v[126:129], v[126:127]
	s_nop 0
	flat_load_dwordx4 v[130:133], v[130:131]
	s_waitcnt vmcnt(0) lgkmcnt(0)
	v_mul_f32_e32 v134, v127, v127
	v_mul_f32_e32 v135, v131, v131
	v_fmac_f32_e32 v134, v126, v126
	v_fmac_f32_e32 v135, v130, v130
	v_fmac_f32_e32 v134, v128, v128
	v_fmac_f32_e32 v135, v132, v132
	v_fmac_f32_e32 v134, v129, v129
	v_fmac_f32_e32 v135, v133, v133
	v_add_f32_e32 v144, v134, v135
	v_add_co_u32_e32 v134, vcc, 0xfffff800, v68
	s_nop 1
	v_addc_co_u32_e32 v135, vcc, -1, v69, vcc
	v_add_co_u32_e32 v138, vcc, 0xfffffc00, v68
	s_nop 1
	v_addc_co_u32_e32 v139, vcc, -1, v69, vcc
	flat_load_dwordx4 v[134:137], v[134:135]
	s_nop 0
	flat_load_dwordx4 v[138:141], v[138:139]
	v_lshl_add_u64 v[68:69], v[68:69], 0, s[10:11]
	s_waitcnt vmcnt(0) lgkmcnt(0)
	v_mul_f32_e32 v145, v135, v135
	v_fmac_f32_e32 v145, v134, v134
	v_fmac_f32_e32 v145, v136, v136
	v_fmac_f32_e32 v145, v137, v137
	v_add_f32_e32 v144, v144, v145
	v_mul_f32_e32 v145, v139, v139
	v_fmac_f32_e32 v145, v138, v138
	v_fmac_f32_e32 v145, v140, v140
	v_fmac_f32_e32 v145, v141, v141
	v_add_f32_e32 v144, v144, v145
	v_add_f32_e32 v114, v144, v114
	v_add_f32_e32 v114, v114, v115
	v_add_f32_e32 v114, v114, v142
	v_add_f32_e32 v114, v114, v143
	ds_bpermute_b32 v115, v0, v114
	s_waitcnt lgkmcnt(0)
	v_add_f32_e32 v114, v114, v115
	ds_bpermute_b32 v115, v117, v114
	s_waitcnt lgkmcnt(0)
	v_add_f32_e32 v114, v114, v115
	s_nop 1
	v_mov_b32_dpp v115, v114 row_shl:8 row_mask:0xf bank_mask:0x3
	v_mov_b32_dpp v115, v114 row_shr:8 row_mask:0xf bank_mask:0xc
	s_waitcnt lgkmcnt(0)
	v_add_f32_e32 v114, v114, v115
	s_nop 1
	v_mov_b32_dpp v115, v114 row_shl:4 row_mask:0xf bank_mask:0x5
	v_mov_b32_dpp v115, v114 row_shr:4 row_mask:0xf bank_mask:0xa
	s_waitcnt lgkmcnt(0)
	v_add_f32_e32 v114, v114, v115
	s_nop 1
	v_mov_b32_dpp v115, v114 quad_perm:[2,3,0,1] row_mask:0xf bank_mask:0xf
	s_waitcnt lgkmcnt(0)
	v_add_f32_e32 v114, v114, v115
	s_nop 1
	v_mov_b32_dpp v115, v114 quad_perm:[1,0,3,2] row_mask:0xf bank_mask:0xf
	s_waitcnt lgkmcnt(0)
; __device__ __forceinline__ unsigned pk2(float lo, float hi) { const f32v2_t v = {lo, hi}; return __builtin_bit_cast(unsigned, __builtin_convertvector(v, bf16v2_t)); }
; __device__ __forceinline__ void norm_phase(const float* __restrict__ xin, const float* __restrict__ gain, const float* __restrict__ shift, const float* __restrict__ scale, bf16_t* __restrict__ H) {
;     ...
;         const float inv = rsqrtf(ss * (1.f / D) + EPS);
; #pragma unroll
;         for (int i = 0; i < 8; ++i) {
;             const int c = i * 256 + lane * 4;
;             const f32x4 g = *(const f32x4*)(gain + c), sh = *(const f32x4*)(shift + c), sc = *(const f32x4*)(scale + c);
;             const f32x4 y = v[i] * inv * g * (1.f + sc) + sh;
;             u32x2 o = {pk2(y[0], y[1]), pk2(y[2], y[3])};
;             *(u32x2*)(H + (size_t)row * D + c) = o;
;         }
	v_add_f32_e32 v114, v114, v115
	v_fmamk_f32 v114, v114, 0x3a000000, v184
	v_mul_f32_e32 v115, 0x4b800000, v114
	v_cmp_gt_f32_e32 vcc, s90, v114
	s_nop 1
	v_cndmask_b32_e32 v114, v114, v115, vcc
	v_rsq_f32_e32 v114, v114
	s_nop 0
	v_mul_f32_e32 v115, 0x45800000, v114
	v_cndmask_b32_e32 v114, v114, v115, vcc
	v_pk_mul_f32 v[128:129], v[128:129], v[114:115] op_sel_hi:[1,0]
	v_pk_mul_f32 v[126:127], v[126:127], v[114:115] op_sel_hi:[1,0]
	v_pk_mul_f32 v[142:143], v[104:105], v[114:115] op_sel_hi:[1,0]
	v_pk_mul_f32 v[144:145], v[102:103], v[114:115] op_sel_hi:[1,0]
	v_pk_mul_f32 v[102:103], v[2:3], v[126:127]
	v_pk_mul_f32 v[104:105], v[4:5], v[128:129]
	v_pk_mul_f32 v[132:133], v[132:133], v[114:115] op_sel_hi:[1,0]
	v_pk_mul_f32 v[130:131], v[130:131], v[114:115] op_sel_hi:[1,0]
	v_pk_fma_f32 v[104:105], v[70:71], v[104:105], v[32:33]
	v_pk_fma_f32 v[102:103], v[72:73], v[102:103], v[30:31]
	v_pk_mul_f32 v[136:137], v[136:137], v[114:115] op_sel_hi:[1,0]
	v_pk_mul_f32 v[134:135], v[134:135], v[114:115] op_sel_hi:[1,0]
	v_pk_mul_f32 v[140:141], v[140:141], v[114:115] op_sel_hi:[1,0]
	v_pk_mul_f32 v[138:139], v[138:139], v[114:115] op_sel_hi:[1,0]
	v_pk_mul_f32 v[146:147], v[108:109], v[114:115] op_sel_hi:[1,0]
	v_pk_mul_f32 v[148:149], v[106:107], v[114:115] op_sel_hi:[1,0]
	v_pk_mul_f32 v[112:113], v[112:113], v[114:115] op_sel_hi:[1,0]
	v_pk_mul_f32 v[150:151], v[110:111], v[114:115] op_sel_hi:[1,0]
	v_pk_mul_f32 v[124:125], v[124:125], v[114:115] op_sel_hi:[1,0]
	v_pk_mul_f32 v[114:115], v[122:123], v[114:115] op_sel_hi:[1,0]
	v_cvt_pk_bf16_f32 v122, v102, v103
	v_cvt_pk_bf16_f32 v123, v104, v105
	v_pk_mul_f32 v[102:103], v[6:7], v[130:131]
	v_pk_mul_f32 v[104:105], v[8:9], v[132:133]
	v_pk_fma_f32 v[102:103], v[76:77], v[102:103], v[34:35]
	v_pk_fma_f32 v[104:105], v[74:75], v[104:105], v[36:37]
	v_cvt_pk_bf16_f32 v102, v102, v103
	v_cvt_pk_bf16_f32 v103, v104, v105
	v_pk_mul_f32 v[104:105], v[10:11], v[134:135]
	v_pk_mul_f32 v[106:107], v[12:13], v[136:137]
	v_pk_fma_f32 v[104:105], v[80:81], v[104:105], v[38:39]
	v_pk_fma_f32 v[106:107], v[78:79], v[106:107], v[40:41]
	v_cvt_pk_bf16_f32 v104, v104, v105
	v_cvt_pk_bf16_f32 v105, v106, v107
	v_pk_mul_f32 v[106:107], v[14:15], v[138:139]
	v_pk_mul_f32 v[108:109], v[16:17], v[140:141]
	v_pk_fma_f32 v[106:107], v[84:85], v[106:107], v[42:43]
	v_pk_fma_f32 v[108:109], v[82:83], v[108:109], v[44:45]
	v_cvt_pk_bf16_f32 v106, v106, v107
	v_cvt_pk_bf16_f32 v107, v108, v109
	v_pk_mul_f32 v[108:109], v[46:47], v[144:145]
	v_pk_mul_f32 v[110:111], v[48:49], v[142:143]
	v_pk_fma_f32 v[108:109], v[88:89], v[108:109], v[18:19]
	v_pk_fma_f32 v[110:111], v[86:87], v[110:111], v[20:21]
	v_cvt_pk_bf16_f32 v108, v108, v109
	v_cvt_pk_bf16_f32 v109, v110, v111
	v_pk_mul_f32 v[110:111], v[50:51], v[148:149]
	v_pk_mul_f32 v[126:127], v[52:53], v[146:147]
	v_pk_fma_f32 v[110:111], v[92:93], v[110:111], v[22:23]
	v_pk_fma_f32 v[126:127], v[90:91], v[126:127], v[24:25]
	v_cvt_pk_bf16_f32 v110, v110, v111
	v_cvt_pk_bf16_f32 v111, v126, v127
	v_pk_mul_f32 v[126:127], v[54:55], v[150:151]
	v_pk_mul_f32 v[112:113], v[56:57], v[112:113]
	v_pk_mul_f32 v[114:115], v[58:59], v[114:115]
	v_pk_mul_f32 v[124:125], v[60:61], v[124:125]
	v_pk_fma_f32 v[128:129], v[94:95], v[112:113], v[28:29]
	v_pk_fma_f32 v[112:113], v[96:97], v[126:127], v[26:27]
	v_pk_fma_f32 v[124:125], v[98:99], v[124:125], v[64:65]
	v_pk_fma_f32 v[114:115], v[100:101], v[114:115], v[62:63]
	v_cmp_lt_i32_e32 vcc, s91, v116
	v_cvt_pk_bf16_f32 v112, v112, v113
	v_cvt_pk_bf16_f32 v113, v128, v129
	v_cvt_pk_bf16_f32 v114, v114, v115
	v_cvt_pk_bf16_f32 v115, v124, v125
	flat_store_dwordx2 v[66:67], v[122:123]
	s_or_b64 s[2:3], vcc, s[2:3]
	flat_store_dwordx2 v[66:67], v[102:103] offset:512
	flat_store_dwordx2 v[66:67], v[104:105] offset:1024
	flat_store_dwordx2 v[66:67], v[106:107] offset:1536
	flat_store_dwordx2 v[66:67], v[108:109] offset:2048
	flat_store_dwordx2 v[66:67], v[110:111] offset:2560
	flat_store_dwordx2 v[66:67], v[112:113] offset:3072
	flat_store_dwordx2 v[66:67], v[114:115] offset:3584
	v_lshl_add_u64 v[66:67], v[66:67], 0, s[6:7]
	s_andn2_b64 exec, exec, s[2:3]
	s_cbranch_execnz .LBB0_172
